# P4a epilogue: 8 read-modify-write MRG loads of add units issued together up front into AGPRs
# speedup vs baseline: 1.1530x; 1.0044x over previous
; __device__ __forceinline__ float bflo(unsigned u) { return __uint_as_float(u << 16); }
; __device__ __forceinline__ float bfhi(unsigned u) { return __uint_as_float(u & 0xffff0000u); }
; __device__ __forceinline__ void phase4a(const Params& p, char* smem) {
;     ...
; #pragma unroll
;         for (int q = 0; q < 8; q++) {
;           const int idx = tid + 256 * q, row = idx >> 4, c8 = idx & 15;
;           uint4 v4 = *(const uint4*)&T[row * 136 + c8 * 8];
;           u16* mp = dbase + (size_t)row * dld + c8 * 8;
;           if (add) {
;             const uint4 o4 = *(const uint4*)mp;
;             v4.x = pack2(bflo(v4.x) + bflo(o4.x), bfhi(v4.x) + bfhi(o4.x));
;             v4.y = pack2(bflo(v4.y) + bflo(o4.y), bfhi(v4.y) + bfhi(o4.y));
;             v4.z = pack2(bflo(v4.z) + bflo(o4.z), bfhi(v4.z) + bfhi(o4.z));
;             v4.w = pack2(bflo(v4.w) + bflo(o4.w), bfhi(v4.w) + bfhi(o4.w));
;           }
;           *(uint4*)mp = v4;
.LBB0_1144:
	ds_read_b128 v[0:3], v24
	v_accvgpr_read_b32 v4, a126
	v_mov_b32_e32 v75, v67
	v_mul_u32_u24_e32 v4, s0, v4
	s_nor_b64 s[16:17], s[16:17], s[22:23]
	v_lshl_add_u64 v[8:9], s[18:19], 0, v[74:75]
	v_lshlrev_b32_e32 v66, 1, v4
	v_lshl_add_u64 v[10:11], v[8:9], 0, v[66:67]
	s_mov_b64 s[18:19], -1
	s_and_b64 vcc, exec, s[16:17]
	v_accvgpr_read_b32 v236, a120
	s_cbranch_vccz .Lp4a_noadd
	global_load_dwordx4 a[196:199], v[10:11], off
	v_accvgpr_read_b32 v12, a135
	v_mul_u32_u24_e32 v12, s0, v12
	v_lshlrev_b32_e32 v66, 1, v12
	v_lshl_add_u64 v[12:13], v[8:9], 0, v[66:67]
	global_load_dwordx4 a[200:203], v[12:13], off
	v_accvgpr_read_b32 v12, a133
	v_mul_u32_u24_e32 v12, s0, v12
	v_lshlrev_b32_e32 v66, 1, v12
	v_lshl_add_u64 v[12:13], v[8:9], 0, v[66:67]
	global_load_dwordx4 a[204:207], v[12:13], off
	v_mul_u32_u24_e32 v12, s0, v236
	v_lshlrev_b32_e32 v66, 1, v12
	v_lshl_add_u64 v[12:13], v[8:9], 0, v[66:67]
	global_load_dwordx4 a[208:211], v[12:13], off
	v_mul_u32_u24_e32 v12, s0, v65
	v_lshlrev_b32_e32 v66, 1, v12
	v_lshl_add_u64 v[12:13], v[8:9], 0, v[66:67]
	global_load_dwordx4 a[212:215], v[12:13], off
	v_accvgpr_read_b32 v12, a99
	v_mul_u32_u24_e32 v12, s0, v12
	v_lshlrev_b32_e32 v66, 1, v12
	v_lshl_add_u64 v[12:13], v[8:9], 0, v[66:67]
	global_load_dwordx4 a[216:219], v[12:13], off
	v_accvgpr_read_b32 v12, a100
	v_mul_u32_u24_e32 v12, s0, v12
	v_lshlrev_b32_e32 v66, 1, v12
	v_lshl_add_u64 v[12:13], v[8:9], 0, v[66:67]
	global_load_dwordx4 a[220:223], v[12:13], off
	v_accvgpr_read_b32 v12, a101
	v_mul_u32_u24_e32 v12, s0, v12
	v_lshlrev_b32_e32 v66, 1, v12
	v_lshl_add_u64 v[12:13], v[8:9], 0, v[66:67]
	global_load_dwordx4 a[224:227], v[12:13], off
.Lp4a_noadd:
	s_cbranch_vccz .LBB0_1146
	s_waitcnt vmcnt(0)
	v_accvgpr_read_b32 v4, a196
	v_accvgpr_read_b32 v5, a197
	v_accvgpr_read_b32 v6, a198
	v_accvgpr_read_b32 v7, a199
	s_waitcnt lgkmcnt(0)
	v_lshlrev_b32_e32 v12, 16, v0
	v_and_b32_e32 v13, 0xffff0000, v0
	v_lshlrev_b32_e32 v14, 16, v1
	v_and_b32_e32 v15, 0xffff0000, v1
	v_lshlrev_b32_e32 v16, 16, v2
	v_and_b32_e32 v17, 0xffff0000, v2
	v_lshlrev_b32_e32 v18, 16, v3
	v_and_b32_e32 v19, 0xffff0000, v3
	s_mov_b64 s[18:19], 0
	v_lshlrev_b32_e32 v20, 16, v4
	v_and_b32_e32 v21, 0xffff0000, v4
	v_lshlrev_b32_e32 v4, 16, v5
	v_and_b32_e32 v5, 0xffff0000, v5
	v_lshlrev_b32_e32 v22, 16, v6
	v_and_b32_e32 v23, 0xffff0000, v6
	v_lshlrev_b32_e32 v6, 16, v7
	v_and_b32_e32 v7, 0xffff0000, v7
	v_pk_add_f32 v[12:13], v[12:13], v[20:21]
	v_pk_add_f32 v[14:15], v[14:15], v[4:5]
	v_pk_add_f32 v[16:17], v[16:17], v[22:23]
	v_pk_add_f32 v[18:19], v[18:19], v[6:7]
	v_cvt_pk_bf16_f32 v4, v12, v13
	v_cvt_pk_bf16_f32 v5, v14, v15
	v_cvt_pk_bf16_f32 v6, v16, v17
	v_cvt_pk_bf16_f32 v7, v18, v19

; __device__ __forceinline__ float bflo(unsigned u) { return __uint_as_float(u << 16); }
; __device__ __forceinline__ float bfhi(unsigned u) { return __uint_as_float(u & 0xffff0000u); }
; __device__ __forceinline__ void phase4a(const Params& p, char* smem) {
;     ...
; #pragma unroll
;         for (int q = 0; q < 8; q++) {
;           const int idx = tid + 256 * q, row = idx >> 4, c8 = idx & 15;
;           uint4 v4 = *(const uint4*)&T[row * 136 + c8 * 8];
;           u16* mp = dbase + (size_t)row * dld + c8 * 8;
;           if (add) {
;             const uint4 o4 = *(const uint4*)mp;
;             v4.x = pack2(bflo(v4.x) + bflo(o4.x), bfhi(v4.x) + bfhi(o4.x));
;             v4.y = pack2(bflo(v4.y) + bflo(o4.y), bfhi(v4.y) + bfhi(o4.y));
;             v4.z = pack2(bflo(v4.z) + bflo(o4.z), bfhi(v4.z) + bfhi(o4.z));
;             v4.w = pack2(bflo(v4.w) + bflo(o4.w), bfhi(v4.w) + bfhi(o4.w));
;           }
;           *(uint4*)mp = v4;
.LBB0_1148:
	s_waitcnt lgkmcnt(0)
	v_accvgpr_read_b32 v0, a121
	ds_read_b128 v[0:3], v0
	global_store_dwordx4 v[10:11], v[4:7], off
	s_mov_b64 s[18:19], -1
	s_and_b64 vcc, exec, s[16:17]
	v_accvgpr_read_b32 v4, a135
	v_mul_u32_u24_e32 v4, s0, v4
	v_lshlrev_b32_e32 v66, 1, v4
	v_lshl_add_u64 v[10:11], v[8:9], 0, v[66:67]
	s_cbranch_vccz .LBB0_1150
	v_accvgpr_read_b32 v4, a200
	v_accvgpr_read_b32 v5, a201
	v_accvgpr_read_b32 v6, a202
	v_accvgpr_read_b32 v7, a203
	s_waitcnt lgkmcnt(0)
	v_lshlrev_b32_e32 v12, 16, v0
	v_and_b32_e32 v13, 0xffff0000, v0
	v_lshlrev_b32_e32 v14, 16, v1
	v_and_b32_e32 v15, 0xffff0000, v1
	v_lshlrev_b32_e32 v16, 16, v2
	v_and_b32_e32 v17, 0xffff0000, v2
	v_lshlrev_b32_e32 v18, 16, v3
	v_and_b32_e32 v19, 0xffff0000, v3
	s_mov_b64 s[18:19], 0
	v_lshlrev_b32_e32 v20, 16, v4
	v_and_b32_e32 v21, 0xffff0000, v4
	v_lshlrev_b32_e32 v4, 16, v5
	v_and_b32_e32 v5, 0xffff0000, v5
	v_lshlrev_b32_e32 v22, 16, v6
	v_and_b32_e32 v23, 0xffff0000, v6
	v_lshlrev_b32_e32 v6, 16, v7
	v_and_b32_e32 v7, 0xffff0000, v7
	v_pk_add_f32 v[12:13], v[12:13], v[20:21]
	v_pk_add_f32 v[14:15], v[14:15], v[4:5]
	v_pk_add_f32 v[16:17], v[16:17], v[22:23]
	v_pk_add_f32 v[18:19], v[18:19], v[6:7]
	v_cvt_pk_bf16_f32 v4, v12, v13
	v_cvt_pk_bf16_f32 v5, v14, v15
	v_cvt_pk_bf16_f32 v6, v16, v17
	v_cvt_pk_bf16_f32 v7, v18, v19

; __device__ __forceinline__ float bflo(unsigned u) { return __uint_as_float(u << 16); }
; __device__ __forceinline__ float bfhi(unsigned u) { return __uint_as_float(u & 0xffff0000u); }
; __device__ __forceinline__ void phase4a(const Params& p, char* smem) {
;     ...
; #pragma unroll
;         for (int q = 0; q < 8; q++) {
;           const int idx = tid + 256 * q, row = idx >> 4, c8 = idx & 15;
;           uint4 v4 = *(const uint4*)&T[row * 136 + c8 * 8];
;           u16* mp = dbase + (size_t)row * dld + c8 * 8;
;           if (add) {
;             const uint4 o4 = *(const uint4*)mp;
;             v4.x = pack2(bflo(v4.x) + bflo(o4.x), bfhi(v4.x) + bfhi(o4.x));
;             v4.y = pack2(bflo(v4.y) + bflo(o4.y), bfhi(v4.y) + bfhi(o4.y));
;             v4.z = pack2(bflo(v4.z) + bflo(o4.z), bfhi(v4.z) + bfhi(o4.z));
;             v4.w = pack2(bflo(v4.w) + bflo(o4.w), bfhi(v4.w) + bfhi(o4.w));
;           }
;           *(uint4*)mp = v4;
.LBB0_1152:
	s_waitcnt lgkmcnt(0)
	v_accvgpr_read_b32 v0, a122
	ds_read_b128 v[0:3], v0
	global_store_dwordx4 v[10:11], v[4:7], off
	s_mov_b64 s[18:19], -1
	s_and_b64 vcc, exec, s[16:17]
	v_accvgpr_read_b32 v4, a133
	v_mul_u32_u24_e32 v4, s0, v4
	v_lshlrev_b32_e32 v66, 1, v4
	v_lshl_add_u64 v[10:11], v[8:9], 0, v[66:67]
	s_cbranch_vccz .LBB0_1154
	v_accvgpr_read_b32 v4, a204
	v_accvgpr_read_b32 v5, a205
	v_accvgpr_read_b32 v6, a206
	v_accvgpr_read_b32 v7, a207
	s_waitcnt lgkmcnt(0)
	v_lshlrev_b32_e32 v12, 16, v0
	v_and_b32_e32 v13, 0xffff0000, v0
	v_lshlrev_b32_e32 v14, 16, v1
	v_and_b32_e32 v15, 0xffff0000, v1
	v_lshlrev_b32_e32 v16, 16, v2
	v_and_b32_e32 v17, 0xffff0000, v2
	v_lshlrev_b32_e32 v18, 16, v3
	v_and_b32_e32 v19, 0xffff0000, v3
	s_mov_b64 s[18:19], 0
	v_lshlrev_b32_e32 v20, 16, v4
	v_and_b32_e32 v21, 0xffff0000, v4
	v_lshlrev_b32_e32 v4, 16, v5
	v_and_b32_e32 v5, 0xffff0000, v5
	v_lshlrev_b32_e32 v22, 16, v6
	v_and_b32_e32 v23, 0xffff0000, v6
	v_lshlrev_b32_e32 v6, 16, v7
	v_and_b32_e32 v7, 0xffff0000, v7
	v_pk_add_f32 v[12:13], v[12:13], v[20:21]
	v_pk_add_f32 v[14:15], v[14:15], v[4:5]
	v_pk_add_f32 v[16:17], v[16:17], v[22:23]
	v_pk_add_f32 v[18:19], v[18:19], v[6:7]
	v_cvt_pk_bf16_f32 v4, v12, v13
	v_cvt_pk_bf16_f32 v5, v14, v15
	v_cvt_pk_bf16_f32 v6, v16, v17
	v_cvt_pk_bf16_f32 v7, v18, v19

; __device__ __forceinline__ float bflo(unsigned u) { return __uint_as_float(u << 16); }
; __device__ __forceinline__ float bfhi(unsigned u) { return __uint_as_float(u & 0xffff0000u); }
; __device__ __forceinline__ void phase4a(const Params& p, char* smem) {
;     ...
; #pragma unroll
;         for (int q = 0; q < 8; q++) {
;           const int idx = tid + 256 * q, row = idx >> 4, c8 = idx & 15;
;           uint4 v4 = *(const uint4*)&T[row * 136 + c8 * 8];
;           u16* mp = dbase + (size_t)row * dld + c8 * 8;
;           if (add) {
;             const uint4 o4 = *(const uint4*)mp;
;             v4.x = pack2(bflo(v4.x) + bflo(o4.x), bfhi(v4.x) + bfhi(o4.x));
;             v4.y = pack2(bflo(v4.y) + bflo(o4.y), bfhi(v4.y) + bfhi(o4.y));
;             v4.z = pack2(bflo(v4.z) + bflo(o4.z), bfhi(v4.z) + bfhi(o4.z));
;             v4.w = pack2(bflo(v4.w) + bflo(o4.w), bfhi(v4.w) + bfhi(o4.w));
;           }
;           *(uint4*)mp = v4;
.LBB0_1156:
	s_waitcnt lgkmcnt(0)
	v_accvgpr_read_b32 v0, a123
	ds_read_b128 v[0:3], v0
	global_store_dwordx4 v[10:11], v[4:7], off
	s_mov_b64 s[18:19], -1
	s_and_b64 vcc, exec, s[16:17]
	v_mul_u32_u24_e32 v4, s0, v236
	v_lshlrev_b32_e32 v66, 1, v4
	v_lshl_add_u64 v[10:11], v[8:9], 0, v[66:67]
	s_cbranch_vccz .LBB0_1158
	v_accvgpr_read_b32 v4, a208
	v_accvgpr_read_b32 v5, a209
	v_accvgpr_read_b32 v6, a210
	v_accvgpr_read_b32 v7, a211
	s_waitcnt lgkmcnt(0)
	v_lshlrev_b32_e32 v12, 16, v0
	v_and_b32_e32 v13, 0xffff0000, v0
	v_lshlrev_b32_e32 v14, 16, v1
	v_and_b32_e32 v15, 0xffff0000, v1
	v_lshlrev_b32_e32 v16, 16, v2
	v_and_b32_e32 v17, 0xffff0000, v2
	v_lshlrev_b32_e32 v18, 16, v3
	v_and_b32_e32 v19, 0xffff0000, v3
	s_mov_b64 s[18:19], 0
	v_lshlrev_b32_e32 v20, 16, v4
	v_and_b32_e32 v21, 0xffff0000, v4
	v_lshlrev_b32_e32 v4, 16, v5
	v_and_b32_e32 v5, 0xffff0000, v5
	v_lshlrev_b32_e32 v22, 16, v6
	v_and_b32_e32 v23, 0xffff0000, v6
	v_lshlrev_b32_e32 v6, 16, v7
	v_and_b32_e32 v7, 0xffff0000, v7
	v_pk_add_f32 v[12:13], v[12:13], v[20:21]
	v_pk_add_f32 v[14:15], v[14:15], v[4:5]
	v_pk_add_f32 v[16:17], v[16:17], v[22:23]
	v_pk_add_f32 v[18:19], v[18:19], v[6:7]
	v_cvt_pk_bf16_f32 v4, v12, v13
	v_cvt_pk_bf16_f32 v5, v14, v15
	v_cvt_pk_bf16_f32 v6, v16, v17
	v_cvt_pk_bf16_f32 v7, v18, v19

; __device__ __forceinline__ float bflo(unsigned u) { return __uint_as_float(u << 16); }
; __device__ __forceinline__ float bfhi(unsigned u) { return __uint_as_float(u & 0xffff0000u); }
; __device__ __forceinline__ void phase4a(const Params& p, char* smem) {
;     ...
; #pragma unroll
;         for (int q = 0; q < 8; q++) {
;           const int idx = tid + 256 * q, row = idx >> 4, c8 = idx & 15;
;           uint4 v4 = *(const uint4*)&T[row * 136 + c8 * 8];
;           u16* mp = dbase + (size_t)row * dld + c8 * 8;
;           if (add) {
;             const uint4 o4 = *(const uint4*)mp;
;             v4.x = pack2(bflo(v4.x) + bflo(o4.x), bfhi(v4.x) + bfhi(o4.x));
;             v4.y = pack2(bflo(v4.y) + bflo(o4.y), bfhi(v4.y) + bfhi(o4.y));
;             v4.z = pack2(bflo(v4.z) + bflo(o4.z), bfhi(v4.z) + bfhi(o4.z));
;             v4.w = pack2(bflo(v4.w) + bflo(o4.w), bfhi(v4.w) + bfhi(o4.w));
;           }
;           *(uint4*)mp = v4;
.LBB0_1160:
	s_waitcnt lgkmcnt(0)
	ds_read_b128 v[0:3], v24 offset:17408
	global_store_dwordx4 v[10:11], v[4:7], off
	s_mov_b64 s[18:19], -1
	s_and_b64 vcc, exec, s[16:17]
	v_mul_u32_u24_e32 v4, s0, v65
	v_lshlrev_b32_e32 v66, 1, v4
	v_lshl_add_u64 v[10:11], v[8:9], 0, v[66:67]
	s_cbranch_vccz .LBB0_1162
	v_accvgpr_read_b32 v4, a212
	v_accvgpr_read_b32 v5, a213
	v_accvgpr_read_b32 v6, a214
	v_accvgpr_read_b32 v7, a215
	s_waitcnt lgkmcnt(0)
	v_lshlrev_b32_e32 v12, 16, v0
	v_and_b32_e32 v13, 0xffff0000, v0
	v_lshlrev_b32_e32 v14, 16, v1
	v_and_b32_e32 v15, 0xffff0000, v1
	v_lshlrev_b32_e32 v16, 16, v2
	v_and_b32_e32 v17, 0xffff0000, v2
	v_lshlrev_b32_e32 v18, 16, v3
	v_and_b32_e32 v19, 0xffff0000, v3
	s_mov_b64 s[18:19], 0
	v_lshlrev_b32_e32 v20, 16, v4
	v_and_b32_e32 v21, 0xffff0000, v4
	v_lshlrev_b32_e32 v4, 16, v5
	v_and_b32_e32 v5, 0xffff0000, v5
	v_lshlrev_b32_e32 v22, 16, v6
	v_and_b32_e32 v23, 0xffff0000, v6
	v_lshlrev_b32_e32 v6, 16, v7
	v_and_b32_e32 v7, 0xffff0000, v7
	v_pk_add_f32 v[12:13], v[12:13], v[20:21]
	v_pk_add_f32 v[14:15], v[14:15], v[4:5]
	v_pk_add_f32 v[16:17], v[16:17], v[22:23]
	v_pk_add_f32 v[18:19], v[18:19], v[6:7]
	v_cvt_pk_bf16_f32 v4, v12, v13
	v_cvt_pk_bf16_f32 v5, v14, v15
	v_cvt_pk_bf16_f32 v6, v16, v17
	v_cvt_pk_bf16_f32 v7, v18, v19

; __device__ __forceinline__ float bflo(unsigned u) { return __uint_as_float(u << 16); }
; __device__ __forceinline__ float bfhi(unsigned u) { return __uint_as_float(u & 0xffff0000u); }
; __device__ __forceinline__ void phase4a(const Params& p, char* smem) {
;     ...
; #pragma unroll
;         for (int q = 0; q < 8; q++) {
;           const int idx = tid + 256 * q, row = idx >> 4, c8 = idx & 15;
;           uint4 v4 = *(const uint4*)&T[row * 136 + c8 * 8];
;           u16* mp = dbase + (size_t)row * dld + c8 * 8;
;           if (add) {
;             const uint4 o4 = *(const uint4*)mp;
;             v4.x = pack2(bflo(v4.x) + bflo(o4.x), bfhi(v4.x) + bfhi(o4.x));
;             v4.y = pack2(bflo(v4.y) + bflo(o4.y), bfhi(v4.y) + bfhi(o4.y));
;             v4.z = pack2(bflo(v4.z) + bflo(o4.z), bfhi(v4.z) + bfhi(o4.z));
;             v4.w = pack2(bflo(v4.w) + bflo(o4.w), bfhi(v4.w) + bfhi(o4.w));
;           }
;           *(uint4*)mp = v4;
.LBB0_1164:
	s_waitcnt lgkmcnt(0)
	v_accvgpr_read_b32 v0, a137
	ds_read_b128 v[0:3], v0
	global_store_dwordx4 v[10:11], v[4:7], off
	s_mov_b64 s[18:19], -1
	s_and_b64 vcc, exec, s[16:17]
	v_accvgpr_read_b32 v4, a99
	v_mul_u32_u24_e32 v4, s0, v4
	v_lshlrev_b32_e32 v66, 1, v4
	v_lshl_add_u64 v[10:11], v[8:9], 0, v[66:67]
	s_cbranch_vccz .LBB0_1166
	v_accvgpr_read_b32 v4, a216
	v_accvgpr_read_b32 v5, a217
	v_accvgpr_read_b32 v6, a218
	v_accvgpr_read_b32 v7, a219
	s_waitcnt lgkmcnt(0)
	v_lshlrev_b32_e32 v12, 16, v0
	v_and_b32_e32 v13, 0xffff0000, v0
	v_lshlrev_b32_e32 v14, 16, v1
	v_and_b32_e32 v15, 0xffff0000, v1
	v_lshlrev_b32_e32 v16, 16, v2
	v_and_b32_e32 v17, 0xffff0000, v2
	v_lshlrev_b32_e32 v18, 16, v3
	v_and_b32_e32 v19, 0xffff0000, v3
	s_mov_b64 s[18:19], 0
	v_lshlrev_b32_e32 v20, 16, v4
	v_and_b32_e32 v21, 0xffff0000, v4
	v_lshlrev_b32_e32 v4, 16, v5
	v_and_b32_e32 v5, 0xffff0000, v5
	v_lshlrev_b32_e32 v22, 16, v6
	v_and_b32_e32 v23, 0xffff0000, v6
	v_lshlrev_b32_e32 v6, 16, v7
	v_and_b32_e32 v7, 0xffff0000, v7
	v_pk_add_f32 v[12:13], v[12:13], v[20:21]
	v_pk_add_f32 v[14:15], v[14:15], v[4:5]
	v_pk_add_f32 v[16:17], v[16:17], v[22:23]
	v_pk_add_f32 v[18:19], v[18:19], v[6:7]
	v_cvt_pk_bf16_f32 v4, v12, v13
	v_cvt_pk_bf16_f32 v5, v14, v15
	v_cvt_pk_bf16_f32 v6, v16, v17
	v_cvt_pk_bf16_f32 v7, v18, v19

; __device__ __forceinline__ float bflo(unsigned u) { return __uint_as_float(u << 16); }
; __device__ __forceinline__ float bfhi(unsigned u) { return __uint_as_float(u & 0xffff0000u); }
; __device__ __forceinline__ void phase4a(const Params& p, char* smem) {
;     ...
; #pragma unroll
;         for (int q = 0; q < 8; q++) {
;           const int idx = tid + 256 * q, row = idx >> 4, c8 = idx & 15;
;           uint4 v4 = *(const uint4*)&T[row * 136 + c8 * 8];
;           u16* mp = dbase + (size_t)row * dld + c8 * 8;
;           if (add) {
;             const uint4 o4 = *(const uint4*)mp;
;             v4.x = pack2(bflo(v4.x) + bflo(o4.x), bfhi(v4.x) + bfhi(o4.x));
;             v4.y = pack2(bflo(v4.y) + bflo(o4.y), bfhi(v4.y) + bfhi(o4.y));
;             v4.z = pack2(bflo(v4.z) + bflo(o4.z), bfhi(v4.z) + bfhi(o4.z));
;             v4.w = pack2(bflo(v4.w) + bflo(o4.w), bfhi(v4.w) + bfhi(o4.w));
;           }
;           *(uint4*)mp = v4;
.LBB0_1168:
	s_waitcnt lgkmcnt(0)
	v_accvgpr_read_b32 v0, a139
	ds_read_b128 v[0:3], v0
	global_store_dwordx4 v[10:11], v[4:7], off
	s_mov_b64 s[18:19], -1
	s_and_b64 vcc, exec, s[16:17]
	v_accvgpr_read_b32 v4, a100
	v_mul_u32_u24_e32 v4, s0, v4
	v_lshlrev_b32_e32 v66, 1, v4
	v_lshl_add_u64 v[10:11], v[8:9], 0, v[66:67]
	s_cbranch_vccz .LBB0_1170
	v_accvgpr_read_b32 v4, a220
	v_accvgpr_read_b32 v5, a221
	v_accvgpr_read_b32 v6, a222
	v_accvgpr_read_b32 v7, a223
	s_waitcnt lgkmcnt(0)
	v_lshlrev_b32_e32 v12, 16, v0
	v_and_b32_e32 v13, 0xffff0000, v0
	v_lshlrev_b32_e32 v14, 16, v1
	v_and_b32_e32 v15, 0xffff0000, v1
	v_lshlrev_b32_e32 v16, 16, v2
	v_and_b32_e32 v17, 0xffff0000, v2
	v_lshlrev_b32_e32 v18, 16, v3
	v_and_b32_e32 v19, 0xffff0000, v3
	s_mov_b64 s[18:19], 0
	v_lshlrev_b32_e32 v20, 16, v4
	v_and_b32_e32 v21, 0xffff0000, v4
	v_lshlrev_b32_e32 v4, 16, v5
	v_and_b32_e32 v5, 0xffff0000, v5
	v_lshlrev_b32_e32 v22, 16, v6
	v_and_b32_e32 v23, 0xffff0000, v6
	v_lshlrev_b32_e32 v6, 16, v7
	v_and_b32_e32 v7, 0xffff0000, v7
	v_pk_add_f32 v[12:13], v[12:13], v[20:21]
	v_pk_add_f32 v[14:15], v[14:15], v[4:5]
	v_pk_add_f32 v[16:17], v[16:17], v[22:23]
	v_pk_add_f32 v[18:19], v[18:19], v[6:7]
	v_cvt_pk_bf16_f32 v4, v12, v13
	v_cvt_pk_bf16_f32 v5, v14, v15
	v_cvt_pk_bf16_f32 v6, v16, v17
	v_cvt_pk_bf16_f32 v7, v18, v19

; __device__ __forceinline__ float bflo(unsigned u) { return __uint_as_float(u << 16); }
; __device__ __forceinline__ float bfhi(unsigned u) { return __uint_as_float(u & 0xffff0000u); }
; __device__ __forceinline__ void phase4a(const Params& p, char* smem) {
;     ...
; #pragma unroll
;         for (int q = 0; q < 8; q++) {
;           const int idx = tid + 256 * q, row = idx >> 4, c8 = idx & 15;
;           uint4 v4 = *(const uint4*)&T[row * 136 + c8 * 8];
;           u16* mp = dbase + (size_t)row * dld + c8 * 8;
;           if (add) {
;             const uint4 o4 = *(const uint4*)mp;
;             v4.x = pack2(bflo(v4.x) + bflo(o4.x), bfhi(v4.x) + bfhi(o4.x));
;             v4.y = pack2(bflo(v4.y) + bflo(o4.y), bfhi(v4.y) + bfhi(o4.y));
;             v4.z = pack2(bflo(v4.z) + bflo(o4.z), bfhi(v4.z) + bfhi(o4.z));
;             v4.w = pack2(bflo(v4.w) + bflo(o4.w), bfhi(v4.w) + bfhi(o4.w));
;           }
;           *(uint4*)mp = v4;
.LBB0_1174:
	v_accvgpr_read_b32 v4, a224
	v_accvgpr_read_b32 v5, a225
	v_accvgpr_read_b32 v6, a226
	v_accvgpr_read_b32 v7, a227
	s_waitcnt lgkmcnt(0)
	v_lshlrev_b32_e32 v10, 16, v0
	v_and_b32_e32 v11, 0xffff0000, v0
	v_lshlrev_b32_e32 v12, 16, v1
	v_and_b32_e32 v13, 0xffff0000, v1
	v_lshlrev_b32_e32 v14, 16, v2
	v_and_b32_e32 v15, 0xffff0000, v2
	v_lshlrev_b32_e32 v16, 16, v3
	v_and_b32_e32 v17, 0xffff0000, v3
	v_lshlrev_b32_e32 v18, 16, v4
	v_and_b32_e32 v19, 0xffff0000, v4
	v_lshlrev_b32_e32 v4, 16, v5
	v_and_b32_e32 v5, 0xffff0000, v5
	v_lshlrev_b32_e32 v20, 16, v6
	v_and_b32_e32 v21, 0xffff0000, v6
	v_lshlrev_b32_e32 v6, 16, v7
	v_and_b32_e32 v7, 0xffff0000, v7
	v_pk_add_f32 v[10:11], v[10:11], v[18:19]
	v_pk_add_f32 v[12:13], v[12:13], v[4:5]
	v_pk_add_f32 v[14:15], v[14:15], v[20:21]
	v_pk_add_f32 v[16:17], v[16:17], v[6:7]
	v_cvt_pk_bf16_f32 v4, v10, v11
	v_cvt_pk_bf16_f32 v5, v12, v13
	v_cvt_pk_bf16_f32 v6, v14, v15
	v_cvt_pk_bf16_f32 v7, v16, v17
	s_cbranch_execnz .LBB0_1123
